# speedup vs baseline: 1.0131x; 1.0003x over previous
; #define tidx() tidx_(wv_)
; __device__ __forceinline__ void phase0_misc(unsigned char* ws, int wv_) {
;     ...
;   {
;     const float* x = inp(ws, 0);
;     const float* g = inp(ws, 2);
;     u16* xg = (u16*)(ws + OFF_XG0);
;     float* ss = (float*)(ws + OFF_SS);
;     int wave = tidx() >> 6, lane = tidx() & 63;
;     for (int row = bidx() * 8 + wave; row < T_; row += gridDim.x * 8) {
;       float sq = 0.f;
;       for (int i = 0; i < 8; ++i) {
;         int col = (i * 64 + lane) * 4;
;         float4 v = *(const float4*)(x + (size_t)row * D_ + col);
;         float4 gg = *(const float4*)(g + col);
.LBB0_151:
	s_or_b64 exec, exec, s[16:17]
	s_add_u32 s4, s78, 0x25140000
	s_addc_u32 s5, s79, 0
	v_mbcnt_lo_u32_b32 v2, -1, 0
	v_mbcnt_hi_u32_b32 v2, -1, v2
	v_writelane_b32 v251, s4, 12
	v_or_b32_e32 v2, s63, v2
	v_ashrrev_i32_e32 v3, 6, v2
	v_writelane_b32 v251, s5, 13
	s_lshl_b32 s4, s62, 3
	v_writelane_b32 v251, s4, 14
	v_add_u32_e32 v10, s4, v3
	s_movk_i32 s4, 0x2000
	v_cmp_gt_i32_e32 vcc, s4, v10
	v_mbcnt_lo_u32_b32 v2, -1, 0
	v_mbcnt_hi_u32_b32 v2, -1, v2
	s_and_saveexec_b64 s[6:7], vcc
	s_cbranch_execz .LBB0_156
	s_load_dwordx2 s[8:9], s[0:1], 0x0
	s_load_dwordx2 s[4:5], s[0:1], 0x10
	v_and_b32_e32 v3, 63, v2
	v_lshlrev_b32_e32 v2, 2, v3
	v_mov_b32_e32 v13, 0
	v_lshlrev_b32_e32 v12, 4, v3
	v_or_b32_e32 v4, 0x400, v2
	s_waitcnt vmcnt(2) lgkmcnt(0)
	v_lshl_add_u64 v[14:15], s[4:5], 0, v[12:13]
	v_lshlrev_b32_e32 v12, 2, v4
	v_or_b32_e32 v6, 0x500, v2
	v_lshl_add_u64 v[16:17], s[4:5], 0, v[12:13]
	v_lshlrev_b32_e32 v12, 2, v6
	v_or_b32_e32 v8, 0x600, v2
	v_lshl_add_u64 v[18:19], s[4:5], 0, v[12:13]
	v_lshlrev_b32_e32 v12, 2, v8
	v_or_b32_e32 v32, 0x700, v2
	v_lshl_add_u64 v[20:21], s[4:5], 0, v[12:13]
	v_lshlrev_b32_e32 v12, 2, v32
	v_lshl_add_u64 v[22:23], s[4:5], 0, v[12:13]
	v_readlane_b32 s4, v251, 12
	v_lshlrev_b32_e32 v12, 3, v3
	v_readlane_b32 s5, v251, 13
	v_xor_b32_e32 v38, 64, v2
	v_xor_b32_e32 v39, 0x80, v2
	v_cmp_eq_u32_e32 vcc, 0, v3
	s_lshl_b32 s14, s39, 3
	v_lshl_add_u64 v[24:25], s[4:5], 0, v[12:13]
	s_mov_b64 s[10:11], 0
	v_lshlrev_b32_e32 v12, 2, v2
	s_movk_i32 s15, 0x7fff
	v_lshlrev_b32_e32 v26, 2, v4
	v_mov_b32_e32 v27, v13
	v_lshlrev_b32_e32 v28, 2, v6
	v_mov_b32_e32 v29, v13
	v_lshlrev_b32_e32 v30, 2, v8
	v_mov_b32_e32 v31, v13
	v_lshlrev_b32_e32 v32, 2, v32
	v_mov_b32_e32 v33, v13
	s_movk_i32 s16, 0x1fff
	v_mov_b32_e32 v40, 1
	global_load_dwordx4 v[112:115], v[14:15], off
	global_load_dwordx4 v[116:119], v[14:15], off offset:1024
	global_load_dwordx4 v[120:123], v[14:15], off offset:2048
	global_load_dwordx4 v[124:127], v[14:15], off offset:3072
	global_load_dwordx4 v[128:131], v[16:17], off
	global_load_dwordx4 v[132:135], v[18:19], off
	global_load_dwordx4 v[136:139], v[20:21], off
	global_load_dwordx4 v[140:143], v[22:23], off
	s_branch .LBB0_154

; __device__ __forceinline__ u32 pack2(float a, float b) { return (u32)f2bf(a) | ((u32)f2bf(b) << 16); }
; __device__ __forceinline__ void phase0_misc(unsigned char* ws, int wv_) {
;     ...
;     for (int row = bidx() * 8 + wave; row < T_; row += gridDim.x * 8) {
;       float sq = 0.f;
;       for (int i = 0; i < 8; ++i) {
;         int col = (i * 64 + lane) * 4;
;         float4 v = *(const float4*)(x + (size_t)row * D_ + col);
;         float4 gg = *(const float4*)(g + col);
;         sq += v.x * v.x + v.y * v.y + v.z * v.z + v.w * v.w;
;         *(uint2*)(xg + (size_t)row * D_ + col) = make_uint2(pack2(v.x * gg.x, v.y * gg.y), pack2(v.z * gg.z, v.w * gg.w));
;       }
.LBB0_154:
	v_ashrrev_i32_e32 v11, 31, v10
	s_waitcnt lgkmcnt(0)
	v_lshlrev_b64 v[2:3], 13, v[10:11]
	v_lshl_add_u64 v[36:37], s[8:9], 0, v[2:3]
	v_lshl_add_u64 v[54:55], v[36:37], 0, v[12:13]
	v_lshlrev_b64 v[34:35], 12, v[10:11]
	v_lshl_add_u64 v[34:35], v[24:25], 0, v[34:35]
	v_lshl_add_u64 v[58:59], v[36:37], 0, v[26:27]
	v_lshl_add_u64 v[62:63], v[36:37], 0, v[28:29]
	v_lshl_add_u64 v[66:67], v[36:37], 0, v[30:31]
	v_lshl_add_u64 v[36:37], v[36:37], 0, v[32:33]
	global_load_dwordx4 v[80:83], v[54:55], off
	global_load_dwordx4 v[84:87], v[54:55], off offset:1024
	global_load_dwordx4 v[88:91], v[54:55], off offset:2048
	global_load_dwordx4 v[92:95], v[54:55], off offset:3072
	global_load_dwordx4 v[96:99], v[58:59], off
	global_load_dwordx4 v[100:103], v[62:63], off
	global_load_dwordx4 v[104:107], v[66:67], off
	global_load_dwordx4 v[108:111], v[36:37], off
	s_waitcnt vmcnt(0)
	v_mov_b64_e32 v[6:7], v[112:113]
	v_mov_b64_e32 v[8:9], v[114:115]
	v_mov_b64_e32 v[2:3], v[80:81]
	v_mov_b64_e32 v[4:5], v[82:83]
	v_pk_mul_f32 v[8:9], v[4:5], v[8:9]
	v_pk_mul_f32 v[6:7], v[2:3], v[6:7]
	v_and_b32_sdwa v43, v9, v40 dst_sel:DWORD dst_unused:UNUSED_PAD src0_sel:WORD_1 src1_sel:DWORD
	v_and_b32_sdwa v44, v7, v40 dst_sel:DWORD dst_unused:UNUSED_PAD src0_sel:WORD_1 src1_sel:DWORD
	v_and_b32_sdwa v41, v8, v40 dst_sel:DWORD dst_unused:UNUSED_PAD src0_sel:WORD_1 src1_sel:DWORD
	v_and_b32_sdwa v42, v6, v40 dst_sel:DWORD dst_unused:UNUSED_PAD src0_sel:WORD_1 src1_sel:DWORD
	v_add3_u32 v9, v9, v43, s15
	v_add3_u32 v7, v7, v44, s15
	v_add3_u32 v6, v6, v42, s15
	v_add3_u32 v8, v8, v41, s15
	v_and_b32_e32 v9, 0xffff0000, v9
	v_and_b32_e32 v41, 0xffff0000, v7
	v_or_b32_sdwa v7, v9, v8 dst_sel:DWORD dst_unused:UNUSED_PAD src0_sel:DWORD src1_sel:WORD_1
	v_or_b32_sdwa v6, v41, v6 dst_sel:DWORD dst_unused:UNUSED_PAD src0_sel:DWORD src1_sel:WORD_1
	global_store_dwordx2 v[34:35], v[6:7], off
	v_mov_b64_e32 v[6:7], v[84:85]
	v_mov_b64_e32 v[8:9], v[86:87]
	s_nop 0
	v_mov_b64_e32 v[42:43], v[116:117]
	v_mov_b64_e32 v[44:45], v[118:119]
	v_pk_mul_f32 v[2:3], v[2:3], v[2:3]
	v_pk_mul_f32 v[4:5], v[4:5], v[4:5]
	v_add_f32_e32 v2, v2, v3
	v_add_f32_e32 v2, v2, v4
	v_pk_mul_f32 v[44:45], v[8:9], v[44:45]
	v_pk_mul_f32 v[42:43], v[6:7], v[42:43]
	v_and_b32_sdwa v41, v44, v40 dst_sel:DWORD dst_unused:UNUSED_PAD src0_sel:WORD_1 src1_sel:DWORD
	v_and_b32_sdwa v47, v45, v40 dst_sel:DWORD dst_unused:UNUSED_PAD src0_sel:WORD_1 src1_sel:DWORD
	v_and_b32_sdwa v48, v43, v40 dst_sel:DWORD dst_unused:UNUSED_PAD src0_sel:WORD_1 src1_sel:DWORD
	v_and_b32_sdwa v46, v42, v40 dst_sel:DWORD dst_unused:UNUSED_PAD src0_sel:WORD_1 src1_sel:DWORD
	v_add3_u32 v41, v44, v41, s15
	v_add3_u32 v44, v45, v47, s15
	v_add3_u32 v43, v43, v48, s15
	v_add3_u32 v42, v42, v46, s15
	v_and_b32_e32 v44, 0xffff0000, v44
	v_and_b32_e32 v45, 0xffff0000, v43
	v_or_b32_sdwa v43, v44, v41 dst_sel:DWORD dst_unused:UNUSED_PAD src0_sel:DWORD src1_sel:WORD_1
	v_or_b32_sdwa v42, v45, v42 dst_sel:DWORD dst_unused:UNUSED_PAD src0_sel:DWORD src1_sel:WORD_1
	global_store_dwordx2 v[34:35], v[42:43], off offset:512
	v_mov_b64_e32 v[42:43], v[88:89]
	v_mov_b64_e32 v[44:45], v[90:91]
	s_nop 0
	v_mov_b64_e32 v[46:47], v[120:121]
	v_mov_b64_e32 v[48:49], v[122:123]
	v_pk_mul_f32 v[48:49], v[44:45], v[48:49]
	v_pk_mul_f32 v[46:47], v[42:43], v[46:47]
	v_and_b32_sdwa v41, v48, v40 dst_sel:DWORD dst_unused:UNUSED_PAD src0_sel:WORD_1 src1_sel:DWORD
	v_and_b32_sdwa v51, v49, v40 dst_sel:DWORD dst_unused:UNUSED_PAD src0_sel:WORD_1 src1_sel:DWORD
	v_and_b32_sdwa v52, v47, v40 dst_sel:DWORD dst_unused:UNUSED_PAD src0_sel:WORD_1 src1_sel:DWORD
	v_and_b32_sdwa v50, v46, v40 dst_sel:DWORD dst_unused:UNUSED_PAD src0_sel:WORD_1 src1_sel:DWORD
	v_add3_u32 v41, v48, v41, s15
	v_add3_u32 v48, v49, v51, s15
	v_add3_u32 v47, v47, v52, s15
	v_add3_u32 v46, v46, v50, s15
	v_and_b32_e32 v48, 0xffff0000, v48
	v_and_b32_e32 v49, 0xffff0000, v47
	v_or_b32_sdwa v47, v48, v41 dst_sel:DWORD dst_unused:UNUSED_PAD src0_sel:DWORD src1_sel:WORD_1
	v_or_b32_sdwa v46, v49, v46 dst_sel:DWORD dst_unused:UNUSED_PAD src0_sel:DWORD src1_sel:WORD_1
	global_store_dwordx2 v[34:35], v[46:47], off offset:1024
	v_mov_b64_e32 v[46:47], v[92:93]
	v_mov_b64_e32 v[48:49], v[94:95]
	s_nop 0
	v_mov_b64_e32 v[50:51], v[124:125]
	v_mov_b64_e32 v[52:53], v[126:127]
	v_pk_mul_f32 v[52:53], v[48:49], v[52:53]
	v_pk_mul_f32 v[50:51], v[46:47], v[50:51]
	v_and_b32_sdwa v41, v52, v40 dst_sel:DWORD dst_unused:UNUSED_PAD src0_sel:WORD_1 src1_sel:DWORD
	v_and_b32_sdwa v55, v53, v40 dst_sel:DWORD dst_unused:UNUSED_PAD src0_sel:WORD_1 src1_sel:DWORD
	v_and_b32_sdwa v56, v51, v40 dst_sel:DWORD dst_unused:UNUSED_PAD src0_sel:WORD_1 src1_sel:DWORD
	v_and_b32_sdwa v54, v50, v40 dst_sel:DWORD dst_unused:UNUSED_PAD src0_sel:WORD_1 src1_sel:DWORD
	v_add3_u32 v41, v52, v41, s15
	v_add3_u32 v52, v53, v55, s15
	v_add3_u32 v51, v51, v56, s15
	v_add3_u32 v50, v50, v54, s15
	v_and_b32_e32 v52, 0xffff0000, v52
	v_and_b32_e32 v53, 0xffff0000, v51
	v_or_b32_sdwa v51, v52, v41 dst_sel:DWORD dst_unused:UNUSED_PAD src0_sel:DWORD src1_sel:WORD_1
	v_or_b32_sdwa v50, v53, v50 dst_sel:DWORD dst_unused:UNUSED_PAD src0_sel:DWORD src1_sel:WORD_1
	global_store_dwordx2 v[34:35], v[50:51], off offset:1536
	v_mov_b64_e32 v[50:51], v[96:97]
	v_mov_b64_e32 v[52:53], v[98:99]
	s_nop 0
	v_mov_b64_e32 v[54:55], v[128:129]
	v_mov_b64_e32 v[56:57], v[130:131]
	v_pk_mul_f32 v[56:57], v[52:53], v[56:57]
	v_pk_mul_f32 v[54:55], v[50:51], v[54:55]
	v_and_b32_sdwa v41, v56, v40 dst_sel:DWORD dst_unused:UNUSED_PAD src0_sel:WORD_1 src1_sel:DWORD
	v_and_b32_sdwa v59, v57, v40 dst_sel:DWORD dst_unused:UNUSED_PAD src0_sel:WORD_1 src1_sel:DWORD
; __device__ __forceinline__ u32 pack2(float a, float b) { return (u32)f2bf(a) | ((u32)f2bf(b) << 16); }
; __device__ __forceinline__ void phase0_misc(unsigned char* ws, int wv_) {
;     ...
;       for (int i = 0; i < 8; ++i) {
;         int col = (i * 64 + lane) * 4;
;         float4 v = *(const float4*)(x + (size_t)row * D_ + col);
;         float4 gg = *(const float4*)(g + col);
;         sq += v.x * v.x + v.y * v.y + v.z * v.z + v.w * v.w;
;         *(uint2*)(xg + (size_t)row * D_ + col) = make_uint2(pack2(v.x * gg.x, v.y * gg.y), pack2(v.z * gg.z, v.w * gg.w));
;       }
;       sq = red16(sq);
;       sq += bperm_xor(sq, lane, 16);
;       sq += bperm_xor(sq, lane, 32);
;       if (lane == 0) ss[row] = sq;
	v_and_b32_sdwa v60, v55, v40 dst_sel:DWORD dst_unused:UNUSED_PAD src0_sel:WORD_1 src1_sel:DWORD
	v_and_b32_sdwa v58, v54, v40 dst_sel:DWORD dst_unused:UNUSED_PAD src0_sel:WORD_1 src1_sel:DWORD
	v_add3_u32 v41, v56, v41, s15
	v_add3_u32 v56, v57, v59, s15
	v_add3_u32 v55, v55, v60, s15
	v_add3_u32 v54, v54, v58, s15
	v_and_b32_e32 v56, 0xffff0000, v56
	v_and_b32_e32 v57, 0xffff0000, v55
	v_or_b32_sdwa v55, v56, v41 dst_sel:DWORD dst_unused:UNUSED_PAD src0_sel:DWORD src1_sel:WORD_1
	v_or_b32_sdwa v54, v57, v54 dst_sel:DWORD dst_unused:UNUSED_PAD src0_sel:DWORD src1_sel:WORD_1
	global_store_dwordx2 v[34:35], v[54:55], off offset:2048
	v_mov_b64_e32 v[54:55], v[100:101]
	v_mov_b64_e32 v[56:57], v[102:103]
	s_nop 0
	v_mov_b64_e32 v[58:59], v[132:133]
	v_mov_b64_e32 v[60:61], v[134:135]
	v_pk_mul_f32 v[60:61], v[56:57], v[60:61]
	v_pk_mul_f32 v[58:59], v[54:55], v[58:59]
	v_and_b32_sdwa v41, v60, v40 dst_sel:DWORD dst_unused:UNUSED_PAD src0_sel:WORD_1 src1_sel:DWORD
	v_and_b32_sdwa v62, v61, v40 dst_sel:DWORD dst_unused:UNUSED_PAD src0_sel:WORD_1 src1_sel:DWORD
	v_and_b32_sdwa v64, v59, v40 dst_sel:DWORD dst_unused:UNUSED_PAD src0_sel:WORD_1 src1_sel:DWORD
	v_and_b32_sdwa v63, v58, v40 dst_sel:DWORD dst_unused:UNUSED_PAD src0_sel:WORD_1 src1_sel:DWORD
	v_add3_u32 v41, v60, v41, s15
	v_add3_u32 v60, v61, v62, s15
	v_add3_u32 v59, v59, v64, s15
	v_add3_u32 v58, v58, v63, s15
	v_and_b32_e32 v60, 0xffff0000, v60
	v_and_b32_e32 v61, 0xffff0000, v59
	v_or_b32_sdwa v59, v60, v41 dst_sel:DWORD dst_unused:UNUSED_PAD src0_sel:DWORD src1_sel:WORD_1
	v_or_b32_sdwa v58, v61, v58 dst_sel:DWORD dst_unused:UNUSED_PAD src0_sel:DWORD src1_sel:WORD_1
	global_store_dwordx2 v[34:35], v[58:59], off offset:2560
	v_mov_b64_e32 v[58:59], v[104:105]
	v_mov_b64_e32 v[60:61], v[106:107]
	s_nop 0
	v_mov_b64_e32 v[62:63], v[136:137]
	v_mov_b64_e32 v[64:65], v[138:139]
	v_pk_mul_f32 v[64:65], v[60:61], v[64:65]
	v_pk_mul_f32 v[62:63], v[58:59], v[62:63]
	v_and_b32_sdwa v41, v64, v40 dst_sel:DWORD dst_unused:UNUSED_PAD src0_sel:WORD_1 src1_sel:DWORD
	v_and_b32_sdwa v66, v65, v40 dst_sel:DWORD dst_unused:UNUSED_PAD src0_sel:WORD_1 src1_sel:DWORD
	v_and_b32_sdwa v68, v63, v40 dst_sel:DWORD dst_unused:UNUSED_PAD src0_sel:WORD_1 src1_sel:DWORD
	v_and_b32_sdwa v67, v62, v40 dst_sel:DWORD dst_unused:UNUSED_PAD src0_sel:WORD_1 src1_sel:DWORD
	v_add3_u32 v41, v64, v41, s15
	v_add3_u32 v64, v65, v66, s15
	v_add3_u32 v63, v63, v68, s15
	v_add3_u32 v62, v62, v67, s15
	v_and_b32_e32 v64, 0xffff0000, v64
	v_and_b32_e32 v65, 0xffff0000, v63
	v_or_b32_sdwa v63, v64, v41 dst_sel:DWORD dst_unused:UNUSED_PAD src0_sel:DWORD src1_sel:WORD_1
	v_or_b32_sdwa v62, v65, v62 dst_sel:DWORD dst_unused:UNUSED_PAD src0_sel:DWORD src1_sel:WORD_1
	global_store_dwordx2 v[34:35], v[62:63], off offset:3072
	v_mov_b64_e32 v[62:63], v[108:109]
	v_mov_b64_e32 v[64:65], v[110:111]
	s_nop 0
	v_mov_b64_e32 v[66:67], v[140:141]
	v_mov_b64_e32 v[68:69], v[142:143]
	v_add_f32_e32 v36, v2, v5
	v_pk_mul_f32 v[4:5], v[6:7], v[6:7]
	v_pk_mul_f32 v[2:3], v[8:9], v[8:9]
	v_add_f32_e32 v4, v4, v5
	v_add_f32_e32 v2, v4, v2
	v_add_f32_e32 v2, v2, v3
	v_pk_mul_f32 v[4:5], v[42:43], v[42:43]
	v_add_f32_e32 v6, v36, v2
	v_pk_mul_f32 v[2:3], v[44:45], v[44:45]
	v_add_f32_e32 v4, v4, v5
	v_add_f32_e32 v2, v4, v2
	v_add_f32_e32 v2, v2, v3
	v_pk_mul_f32 v[4:5], v[46:47], v[46:47]
	v_add_f32_e32 v6, v6, v2
	v_pk_mul_f32 v[2:3], v[48:49], v[48:49]
	v_add_f32_e32 v4, v4, v5
	v_add_f32_e32 v2, v4, v2
	v_add_f32_e32 v2, v2, v3
	v_pk_mul_f32 v[4:5], v[50:51], v[50:51]
	v_add_f32_e32 v6, v6, v2
	v_pk_mul_f32 v[2:3], v[52:53], v[52:53]
	v_add_f32_e32 v4, v4, v5
	v_add_f32_e32 v2, v4, v2
	v_add_f32_e32 v2, v2, v3
	v_pk_mul_f32 v[4:5], v[54:55], v[54:55]
	v_add_f32_e32 v6, v6, v2
	v_pk_mul_f32 v[2:3], v[56:57], v[56:57]
	v_add_f32_e32 v4, v4, v5
	v_add_f32_e32 v2, v4, v2
	v_add_f32_e32 v2, v2, v3
	v_pk_mul_f32 v[4:5], v[58:59], v[58:59]
	v_add_f32_e32 v6, v6, v2
	v_pk_mul_f32 v[2:3], v[60:61], v[60:61]
	v_add_f32_e32 v4, v4, v5
	v_add_f32_e32 v2, v4, v2
	v_add_f32_e32 v2, v2, v3
	v_add_f32_e32 v36, v6, v2
	v_pk_mul_f32 v[4:5], v[62:63], v[62:63]
	v_pk_mul_f32 v[2:3], v[64:65], v[64:65]
	v_add_f32_e32 v4, v4, v5
	v_add_f32_e32 v2, v4, v2
	v_add_f32_e32 v2, v2, v3
	v_add_f32_e32 v2, v36, v2
	v_pk_mul_f32 v[6:7], v[64:65], v[68:69]
	v_pk_mul_f32 v[8:9], v[62:63], v[66:67]
	v_add_f32_dpp v2, v2, v2 quad_perm:[1,0,3,2] row_mask:0xf bank_mask:0xf bound_ctrl:1
	v_and_b32_sdwa v5, v6, v40 dst_sel:DWORD dst_unused:UNUSED_PAD src0_sel:WORD_1 src1_sel:DWORD
	v_add3_u32 v5, v6, v5, s15
	v_add_f32_dpp v2, v2, v2 quad_perm:[2,3,0,1] row_mask:0xf bank_mask:0xf bound_ctrl:1
	v_and_b32_sdwa v37, v8, v40 dst_sel:DWORD dst_unused:UNUSED_PAD src0_sel:WORD_1 src1_sel:DWORD
	v_and_b32_sdwa v3, v7, v40 dst_sel:DWORD dst_unused:UNUSED_PAD src0_sel:WORD_1 src1_sel:DWORD
	v_add_f32_dpp v2, v2, v2 row_half_mirror row_mask:0xf bank_mask:0xf bound_ctrl:1
	v_add3_u32 v4, v8, v37, s15
	v_and_b32_sdwa v8, v9, v40 dst_sel:DWORD dst_unused:UNUSED_PAD src0_sel:WORD_1 src1_sel:DWORD
	v_add_f32_dpp v2, v2, v2 row_mirror row_mask:0xf bank_mask:0xf bound_ctrl:1
	ds_bpermute_b32 v6, v38, v2
	v_add3_u32 v3, v7, v3, s15
	v_add3_u32 v7, v9, v8, s15
	v_and_b32_e32 v8, 0xffff0000, v3
	v_or_b32_sdwa v5, v8, v5 dst_sel:DWORD dst_unused:UNUSED_PAD src0_sel:DWORD src1_sel:WORD_1
	s_waitcnt lgkmcnt(0)
	v_add_f32_e32 v2, v2, v6
	ds_bpermute_b32 v3, v39, v2
	v_and_b32_e32 v6, 0xffff0000, v7
	v_or_b32_sdwa v4, v6, v4 dst_sel:DWORD dst_unused:UNUSED_PAD src0_sel:DWORD src1_sel:WORD_1
	global_store_dwordx2 v[34:35], v[4:5], off offset:3584
	s_and_saveexec_b64 s[4:5], vcc
	s_cbranch_execz .LBB0_153
	s_waitcnt lgkmcnt(0)
	v_add_f32_e32 v4, v2, v3
	v_lshl_add_u64 v[2:3], v[10:11], 2, s[12:13]
	global_store_dword v[2:3], v4, off
	s_branch .LBB0_153
